# PH6 SwiGLU epilogue: all per-row-group vmcnt(0) waits removed after hoisting the ssqX loads (the 8 ACT stores now stream; the next tile's K loop counted waits retire them in issue order)
# baseline (speedup 1.0000x reference)
; __device__ __forceinline__ void st8(bf16_t* p, f32x4 a, f32x4 b) { u32x4 w; w.x = cvt_pk_bf16(a[0], a[1]); w.y = cvt_pk_bf16(a[2], a[3]); w.z = cvt_pk_bf16(b[0], b[1]); w.w = cvt_pk_bf16(b[2], b[3]); *(u32x4*)p = w; }
;     __device__ __forceinline__ void operator()(const f32x4 (&acc)[2][2][4][2], const Unit& u, int wr, int wc, int fr, int fq) const {
;         asm volatile("" : "+v"(fr), "+v"(fq)); asm volatile("" : "+s"(wr), "+s"(wc));
;         const int rl0 = wr * 64 + fr, pn = u.pn, cw = wc * 32 + fq * 8;
;         bf16_t* base = (u.pm < pm_split) ? ACT1 + (size_t)u.pm * BM * 2816 : ACT2 + (size_t)(u.pm - pm_split) * BM * 2816;
; #pragma unroll
;         for (int ai = 0; ai < 2; ++ai)
; #pragma unroll
;             for (int m = 0; m < 4; ++m) {
;                 const int rl = rl0 + ai * HALF + m * 16;
;                 const float s = rsqrtf(ssqX[u.pm * BM + rl] * (1.0f / 1024.0f) + EPS);
;                 f32x4 o[2];
; #pragma unroll
;                 for (int n = 0; n < 2; ++n) {
;                     const f32x4 g = acc[ai][0][m][n] * s, up = acc[ai][1][m][n] * s;
; #pragma unroll
;                     for (int j = 0; j < 4; ++j) { const float e = __builtin_amdgcn_exp2f(g[j] * -1.4426950408889634f); o[n][j] = g[j] * __builtin_amdgcn_rcpf(1.0f + e) * up[j]; }
;                 }
;                 st8(base + (size_t)rl * 2816 + pn * 128 + cw, o[0], o[1]);
;                 asm volatile("" ::: "memory");
.LBB0_815:
	s_add_i32 s23, s28, 0xffffff76
	s_ashr_i32 s30, s28, 31
	s_cmpk_lt_i32 s28, 0x8a
	s_cselect_b32 s23, s28, s23
	s_cselect_b32 s30, s30, 0
	s_mul_i32 s30, s30, 0x160000
	s_mul_hi_u32 s35, s23, 0x160000
	v_mov_b32_e32 v156, v145
	v_mov_b32_e32 v151, v144
	s_mov_b32 s4, s42
	s_mov_b32 s5, s52
	s_cselect_b32 s31, s49, s7
	s_cselect_b32 s34, s48, s6
	s_add_i32 s35, s35, s30
	s_mul_i32 s23, s23, 0x160000
	s_add_u32 s23, s34, s23
	s_addc_u32 s34, s31, s35
	v_lshl_add_u32 v151, s4, 6, v151
	s_lshl_b32 s4, s28, 8
	v_add_u32_e32 v152, s4, v151
	v_ashrrev_i32_e32 v153, 31, v152
	v_lshl_add_u64 v[152:153], v[152:153], 2, s[14:15]
	global_load_dword v157, v[152:153], off
	global_load_dword v240, v[152:153], off offset:64
	global_load_dword v241, v[152:153], off offset:128
	global_load_dword v242, v[152:153], off offset:192
	global_load_dword v243, v[152:153], off offset:512
	global_load_dword v244, v[152:153], off offset:576
	global_load_dword v245, v[152:153], off offset:640
	global_load_dword v246, v[152:153], off offset:704
	v_mov_b32_e32 v154, v122
	v_mov_b32_e32 v155, v114
	v_mov_b32_e32 v114, v123
	v_mov_b32_e32 v152, v124
	v_mov_b32_e32 v124, v126
	v_mov_b32_e32 v126, v120
	v_lshlrev_b32_e32 v120, 3, v156
	v_mov_b32_e32 v153, v116
	v_mov_b32_e32 v116, v125
	v_mov_b32_e32 v125, v118
	v_mov_b32_e32 v118, v127
	v_mov_b32_e32 v127, v112
	v_mov_b32_e32 v112, v121
	s_lshl_b32 s30, s61, 7
	s_ashr_i32 s31, s30, 31
	s_lshl_b64 s[30:31], s[30:31], 1
	v_lshl_add_u32 v120, s5, 5, v120
	s_add_u32 s30, s23, s30
	v_ashrrev_i32_e32 v121, 31, v120
	s_addc_u32 s31, s34, s31
	v_lshl_add_u64 v[120:121], v[120:121], 1, s[30:31]
	s_waitcnt vmcnt(0)
	v_fmamk_f32 v122, v157, 0x3a800000, v150
	v_mul_f32_e32 v123, 0x4b800000, v122
	v_cmp_gt_f32_e32 vcc, s58, v122
	s_nop 1
	v_cndmask_b32_e32 v122, v122, v123, vcc
	v_rsq_f32_e32 v156, v122
	v_mad_i64_i32 v[122:123], s[30:31], v151, s59, v[120:121]
	v_mul_f32_e32 v157, 0x45800000, v156
	v_cndmask_b32_e32 v156, v156, v157, vcc
	v_pk_mul_f32 v[152:153], v[152:153], v[156:157] op_sel_hi:[1,0]
	v_pk_mul_f32 v[116:117], v[116:117], v[156:157] op_sel_hi:[1,0]
	v_pk_mul_f32 v[124:125], v[124:125], v[156:157] op_sel_hi:[1,0]
	v_pk_mul_f32 v[118:119], v[118:119], v[156:157] op_sel_hi:[1,0]
	v_pk_mul_f32 v[126:127], v[126:127], v[156:157] op_sel_hi:[1,0]
	v_pk_mul_f32 v[112:113], v[112:113], v[156:157] op_sel_hi:[1,0]
	v_pk_mul_f32 v[114:115], v[114:115], v[156:157] op_sel_hi:[1,0]
	v_pk_mul_f32 v[154:155], v[154:155], v[156:157] op_sel_hi:[1,0]
	v_mul_f32_e32 v156, 0xbfb8aa3b, v153
	v_mul_f32_e32 v157, 0xbfb8aa3b, v117
	v_mul_f32_e32 v158, 0xbfb8aa3b, v125
	v_mul_f32_e32 v159, 0xbfb8aa3b, v119
	v_mul_f32_e32 v160, 0xbfb8aa3b, v127
	v_mul_f32_e32 v161, 0xbfb8aa3b, v113
	v_mul_f32_e32 v163, 0xbfb8aa3b, v115
	v_mul_f32_e32 v162, 0xbfb8aa3b, v155
	v_exp_f32_e32 v156, v156
	v_exp_f32_e32 v157, v157
	v_exp_f32_e32 v158, v158
	v_exp_f32_e32 v159, v159
	v_exp_f32_e32 v160, v160
	v_exp_f32_e32 v161, v161
	v_exp_f32_e32 v163, v163
	v_exp_f32_e32 v162, v162
	v_add_f32_e32 v156, 1.0, v156
	v_add_f32_e32 v157, 1.0, v157
	v_add_f32_e32 v158, 1.0, v158
	v_add_f32_e32 v159, 1.0, v159
	v_add_f32_e32 v160, 1.0, v160
	v_add_f32_e32 v161, 1.0, v161
	v_add_f32_e32 v163, 1.0, v163
	v_add_f32_e32 v162, 1.0, v162
	v_rcp_f32_e32 v156, v156
	v_rcp_f32_e32 v157, v157
	v_rcp_f32_e32 v158, v158
	v_rcp_f32_e32 v159, v159
	v_rcp_f32_e32 v160, v160
	v_rcp_f32_e32 v161, v161
	v_rcp_f32_e32 v163, v163
	v_rcp_f32_e32 v162, v162
	v_mul_f32_e32 v153, v153, v156
	v_mul_f32_e32 v117, v117, v157
	v_mul_f32_e32 v125, v125, v158
	v_mul_f32_e32 v119, v119, v159
	v_mul_f32_e32 v127, v127, v160
	v_mul_f32_e32 v113, v113, v161
	v_mul_f32_e32 v115, v115, v163
	v_mul_f32_e32 v155, v155, v162
	v_mul_f32_e32 v152, v152, v153
	v_mul_f32_e32 v116, v116, v117
	v_mul_f32_e32 v117, v124, v125
	v_mul_f32_e32 v118, v118, v119
	v_mul_f32_e32 v119, v126, v127
	v_mul_f32_e32 v124, v112, v113
	v_mul_f32_e32 v115, v114, v115
	v_cvt_pk_bf16_f32 v112, v152, v116
	v_cvt_pk_bf16_f32 v113, v117, v118
	v_cvt_pk_bf16_f32 v114, v119, v124
	v_mul_f32_e32 v125, v154, v155
	v_cvt_pk_bf16_f32 v115, v125, v115
	global_store_dwordx4 v[122:123], v[112:115], off
	v_add_u32_e32 v117, 32, v151
	s_nop 0
	v_add_u32_e32 v114, 16, v151
	v_add_u32_e32 v112, s4, v114
	v_ashrrev_i32_e32 v113, 31, v112
	v_lshl_add_u64 v[112:113], v[112:113], 2, s[14:15]
	s_nop 1
	v_mov_b32_e32 v115, v240
	v_mov_b32_e32 v113, v100
	v_mov_b32_e32 v100, v109
	v_mov_b32_e32 v109, v102
	v_mov_b32_e32 v102, v111
	v_mov_b32_e32 v111, v96
	v_mov_b32_e32 v96, v105
	v_mov_b32_e32 v105, v98
	v_mov_b32_e32 v98, v107
	v_mov_b32_e32 v112, v108
	v_mov_b32_e32 v108, v110
	v_mov_b32_e32 v110, v104
	v_mov_b32_e32 v104, v106
	v_add_u32_e32 v106, s4, v117
	v_ashrrev_i32_e32 v107, 31, v106
	v_lshl_add_u64 v[106:107], v[106:107], 2, s[14:15]
	v_fmamk_f32 v115, v115, 0x3a800000, v150
	v_mul_f32_e32 v116, 0x4b800000, v115
	v_cmp_gt_f32_e32 vcc, s58, v115
	s_nop 1
	v_cndmask_b32_e32 v115, v115, v116, vcc
	v_rsq_f32_e32 v116, v115
	v_mad_i64_i32 v[114:115], s[30:31], v114, s59, v[120:121]
	v_mul_f32_e32 v118, 0x45800000, v116
	v_cndmask_b32_e32 v116, v116, v118, vcc
	v_pk_mul_f32 v[98:99], v[98:99], v[116:117] op_sel_hi:[1,0]
	v_pk_mul_f32 v[112:113], v[112:113], v[116:117] op_sel_hi:[1,0]
	v_pk_mul_f32 v[100:101], v[100:101], v[116:117] op_sel_hi:[1,0]
	v_pk_mul_f32 v[108:109], v[108:109], v[116:117] op_sel_hi:[1,0]
	v_pk_mul_f32 v[102:103], v[102:103], v[116:117] op_sel_hi:[1,0]
	v_pk_mul_f32 v[110:111], v[110:111], v[116:117] op_sel_hi:[1,0]
	v_pk_mul_f32 v[96:97], v[96:97], v[116:117] op_sel_hi:[1,0]
	v_pk_mul_f32 v[104:105], v[104:105], v[116:117] op_sel_hi:[1,0]
; __device__ __forceinline__ void st8(bf16_t* p, f32x4 a, f32x4 b) { u32x4 w; w.x = cvt_pk_bf16(a[0], a[1]); w.y = cvt_pk_bf16(a[2], a[3]); w.z = cvt_pk_bf16(b[0], b[1]); w.w = cvt_pk_bf16(b[2], b[3]); *(u32x4*)p = w; }
;     __device__ __forceinline__ void operator()(const f32x4 (&acc)[2][2][4][2], const Unit& u, int wr, int wc, int fr, int fq) const {
;     ...
;                 const int rl = rl0 + ai * HALF + m * 16;
;                 const float s = rsqrtf(ssqX[u.pm * BM + rl] * (1.0f / 1024.0f) + EPS);
;                 f32x4 o[2];
; #pragma unroll
;                 for (int n = 0; n < 2; ++n) {
;                     const f32x4 g = acc[ai][0][m][n] * s, up = acc[ai][1][m][n] * s;
; #pragma unroll
;                     for (int j = 0; j < 4; ++j) { const float e = __builtin_amdgcn_exp2f(g[j] * -1.4426950408889634f); o[n][j] = g[j] * __builtin_amdgcn_rcpf(1.0f + e) * up[j]; }
;                 }
;                 st8(base + (size_t)rl * 2816 + pn * 128 + cw, o[0], o[1]);
;                 asm volatile("" ::: "memory");
	v_mul_f32_e32 v126, 0xbfb8aa3b, v99
	v_mul_f32_e32 v116, 0xbfb8aa3b, v113
	v_mul_f32_e32 v118, 0xbfb8aa3b, v101
	v_mul_f32_e32 v119, 0xbfb8aa3b, v109
	v_mul_f32_e32 v122, 0xbfb8aa3b, v103
	v_mul_f32_e32 v123, 0xbfb8aa3b, v111
	v_mul_f32_e32 v124, 0xbfb8aa3b, v97
	v_mul_f32_e32 v125, 0xbfb8aa3b, v105
	v_exp_f32_e32 v126, v126
	v_exp_f32_e32 v116, v116
	v_exp_f32_e32 v118, v118
	v_exp_f32_e32 v119, v119
	v_exp_f32_e32 v122, v122
	v_exp_f32_e32 v123, v123
	v_exp_f32_e32 v124, v124
	v_exp_f32_e32 v125, v125
	v_add_f32_e32 v126, 1.0, v126
	v_add_f32_e32 v116, 1.0, v116
	v_add_f32_e32 v118, 1.0, v118
	v_add_f32_e32 v119, 1.0, v119
	v_add_f32_e32 v122, 1.0, v122
	v_add_f32_e32 v123, 1.0, v123
	v_add_f32_e32 v124, 1.0, v124
	v_add_f32_e32 v125, 1.0, v125
	v_rcp_f32_e32 v126, v126
	v_rcp_f32_e32 v116, v116
	v_rcp_f32_e32 v118, v118
	v_rcp_f32_e32 v119, v119
	v_rcp_f32_e32 v122, v122
	v_rcp_f32_e32 v123, v123
	v_rcp_f32_e32 v124, v124
	v_rcp_f32_e32 v125, v125
	v_mul_f32_e32 v99, v99, v126
	v_mul_f32_e32 v113, v113, v116
	v_mul_f32_e32 v101, v101, v118
	v_mul_f32_e32 v109, v109, v119
	v_mul_f32_e32 v103, v103, v122
	v_mul_f32_e32 v111, v111, v123
	v_mul_f32_e32 v97, v97, v124
	v_mul_f32_e32 v105, v105, v125
	v_mul_f32_e32 v99, v98, v99
	v_mul_f32_e32 v112, v112, v113
	v_mul_f32_e32 v100, v100, v101
	v_mul_f32_e32 v101, v108, v109
	v_mul_f32_e32 v102, v102, v103
	v_mul_f32_e32 v103, v110, v111
	v_mul_f32_e32 v108, v96, v97
	v_mul_f32_e32 v104, v104, v105
	v_cvt_pk_bf16_f32 v96, v112, v100
	v_cvt_pk_bf16_f32 v97, v101, v102
	v_cvt_pk_bf16_f32 v98, v103, v108
	v_cvt_pk_bf16_f32 v99, v104, v99
	global_store_dwordx4 v[114:115], v[96:99], off
	s_nop 1
	v_mov_b32_e32 v98, v241
	v_add_u32_e32 v101, 48, v151
	v_mov_b32_e32 v97, v84
	v_mov_b32_e32 v84, v93
	v_mov_b32_e32 v93, v86
	v_mov_b32_e32 v86, v95
	v_mov_b32_e32 v95, v80
	v_mov_b32_e32 v80, v89
	v_mov_b32_e32 v89, v82
	v_mov_b32_e32 v82, v91
	v_mov_b32_e32 v96, v92
	v_mov_b32_e32 v92, v94
	v_mov_b32_e32 v94, v88
	v_mov_b32_e32 v88, v90
	v_add_u32_e32 v90, s4, v101
	v_ashrrev_i32_e32 v91, 31, v90
	v_lshl_add_u64 v[90:91], v[90:91], 2, s[14:15]
	v_fmamk_f32 v98, v98, 0x3a800000, v150
	v_mul_f32_e32 v99, 0x4b800000, v98
	v_cmp_gt_f32_e32 vcc, s58, v98
	s_nop 1
	v_cndmask_b32_e32 v98, v98, v99, vcc
	v_rsq_f32_e32 v100, v98
	v_mad_i64_i32 v[98:99], s[30:31], v117, s59, v[120:121]
	v_mul_f32_e32 v102, 0x45800000, v100
	v_cndmask_b32_e32 v100, v100, v102, vcc
	v_pk_mul_f32 v[82:83], v[82:83], v[100:101] op_sel_hi:[1,0]
	v_pk_mul_f32 v[96:97], v[96:97], v[100:101] op_sel_hi:[1,0]
	v_pk_mul_f32 v[84:85], v[84:85], v[100:101] op_sel_hi:[1,0]
	v_pk_mul_f32 v[92:93], v[92:93], v[100:101] op_sel_hi:[1,0]
	v_pk_mul_f32 v[86:87], v[86:87], v[100:101] op_sel_hi:[1,0]
	v_pk_mul_f32 v[94:95], v[94:95], v[100:101] op_sel_hi:[1,0]
	v_pk_mul_f32 v[80:81], v[80:81], v[100:101] op_sel_hi:[1,0]
	v_pk_mul_f32 v[88:89], v[88:89], v[100:101] op_sel_hi:[1,0]
	v_mul_f32_e32 v108, 0xbfb8aa3b, v83
	v_mul_f32_e32 v100, 0xbfb8aa3b, v97
	v_mul_f32_e32 v102, 0xbfb8aa3b, v85
	v_mul_f32_e32 v103, 0xbfb8aa3b, v93
	v_mul_f32_e32 v104, 0xbfb8aa3b, v87
	v_mul_f32_e32 v105, 0xbfb8aa3b, v95
	v_mul_f32_e32 v106, 0xbfb8aa3b, v81
	v_mul_f32_e32 v107, 0xbfb8aa3b, v89
	v_exp_f32_e32 v108, v108
	v_exp_f32_e32 v100, v100
	v_exp_f32_e32 v102, v102
	v_exp_f32_e32 v103, v103
	v_exp_f32_e32 v104, v104
	v_exp_f32_e32 v105, v105
	v_exp_f32_e32 v106, v106
	v_exp_f32_e32 v107, v107
	v_add_f32_e32 v108, 1.0, v108
	v_add_f32_e32 v100, 1.0, v100
	v_add_f32_e32 v102, 1.0, v102
	v_add_f32_e32 v103, 1.0, v103
	v_add_f32_e32 v104, 1.0, v104
	v_add_f32_e32 v105, 1.0, v105
	v_add_f32_e32 v106, 1.0, v106
	v_add_f32_e32 v107, 1.0, v107
	v_rcp_f32_e32 v108, v108
	v_rcp_f32_e32 v100, v100
	v_rcp_f32_e32 v102, v102
	v_rcp_f32_e32 v103, v103
	v_rcp_f32_e32 v104, v104
	v_rcp_f32_e32 v105, v105
	v_rcp_f32_e32 v106, v106
	v_rcp_f32_e32 v107, v107
	v_mul_f32_e32 v83, v83, v108
	v_mul_f32_e32 v97, v97, v100
	v_mul_f32_e32 v85, v85, v102
	v_mul_f32_e32 v93, v93, v103
	v_mul_f32_e32 v87, v87, v104
	v_mul_f32_e32 v95, v95, v105
	v_mul_f32_e32 v81, v81, v106
	v_mul_f32_e32 v89, v89, v107
	v_mul_f32_e32 v83, v82, v83
	v_mul_f32_e32 v96, v96, v97
	v_mul_f32_e32 v84, v84, v85
	v_mul_f32_e32 v85, v92, v93
	v_mul_f32_e32 v86, v86, v87
	v_mul_f32_e32 v87, v94, v95
	v_mul_f32_e32 v92, v80, v81
	v_mul_f32_e32 v88, v88, v89
	v_cvt_pk_bf16_f32 v80, v96, v84
	v_cvt_pk_bf16_f32 v81, v85, v86
	v_cvt_pk_bf16_f32 v82, v87, v92
	v_cvt_pk_bf16_f32 v83, v88, v83
	global_store_dwordx4 v[98:99], v[80:83], off
	s_nop 1
	v_mov_b32_e32 v82, v242
	v_add_u32_e32 v85, 0x80, v151
	v_mov_b32_e32 v81, v68
	v_mov_b32_e32 v68, v77
	v_mov_b32_e32 v77, v70
	v_mov_b32_e32 v70, v79
	v_mov_b32_e32 v79, v64
	v_mov_b32_e32 v64, v73
	v_mov_b32_e32 v73, v66
	v_mov_b32_e32 v66, v75
	v_mov_b32_e32 v80, v76
	v_mov_b32_e32 v76, v78
	v_mov_b32_e32 v78, v72
	v_mov_b32_e32 v72, v74
	v_add_u32_e32 v74, s4, v85
	v_ashrrev_i32_e32 v75, 31, v74
	v_lshl_add_u64 v[74:75], v[74:75], 2, s[14:15]
	v_fmamk_f32 v82, v82, 0x3a800000, v150
	v_mul_f32_e32 v83, 0x4b800000, v82
	v_cmp_gt_f32_e32 vcc, s58, v82
	s_nop 1
	v_cndmask_b32_e32 v82, v82, v83, vcc
	v_rsq_f32_e32 v84, v82
	v_mad_i64_i32 v[82:83], s[30:31], v101, s59, v[120:121]
	v_mul_f32_e32 v86, 0x45800000, v84
	v_cndmask_b32_e32 v84, v84, v86, vcc
	v_pk_mul_f32 v[66:67], v[66:67], v[84:85] op_sel_hi:[1,0]
	v_pk_mul_f32 v[80:81], v[80:81], v[84:85] op_sel_hi:[1,0]
	v_pk_mul_f32 v[68:69], v[68:69], v[84:85] op_sel_hi:[1,0]
	v_pk_mul_f32 v[76:77], v[76:77], v[84:85] op_sel_hi:[1,0]
	v_pk_mul_f32 v[70:71], v[70:71], v[84:85] op_sel_hi:[1,0]
	v_pk_mul_f32 v[78:79], v[78:79], v[84:85] op_sel_hi:[1,0]
; __device__ __forceinline__ void st8(bf16_t* p, f32x4 a, f32x4 b) { u32x4 w; w.x = cvt_pk_bf16(a[0], a[1]); w.y = cvt_pk_bf16(a[2], a[3]); w.z = cvt_pk_bf16(b[0], b[1]); w.w = cvt_pk_bf16(b[2], b[3]); *(u32x4*)p = w; }
;     __device__ __forceinline__ void operator()(const f32x4 (&acc)[2][2][4][2], const Unit& u, int wr, int wc, int fr, int fq) const {
;     ...
;                 const int rl = rl0 + ai * HALF + m * 16;
;                 const float s = rsqrtf(ssqX[u.pm * BM + rl] * (1.0f / 1024.0f) + EPS);
;                 f32x4 o[2];
; #pragma unroll
;                 for (int n = 0; n < 2; ++n) {
;                     const f32x4 g = acc[ai][0][m][n] * s, up = acc[ai][1][m][n] * s;
; #pragma unroll
;                     for (int j = 0; j < 4; ++j) { const float e = __builtin_amdgcn_exp2f(g[j] * -1.4426950408889634f); o[n][j] = g[j] * __builtin_amdgcn_rcpf(1.0f + e) * up[j]; }
;                 }
;                 st8(base + (size_t)rl * 2816 + pn * 128 + cw, o[0], o[1]);
;                 asm volatile("" ::: "memory");
	v_pk_mul_f32 v[64:65], v[64:65], v[84:85] op_sel_hi:[1,0]
	v_pk_mul_f32 v[72:73], v[72:73], v[84:85] op_sel_hi:[1,0]
	v_mul_f32_e32 v92, 0xbfb8aa3b, v67
	v_mul_f32_e32 v84, 0xbfb8aa3b, v81
	v_mul_f32_e32 v86, 0xbfb8aa3b, v69
	v_mul_f32_e32 v87, 0xbfb8aa3b, v77
	v_mul_f32_e32 v88, 0xbfb8aa3b, v71
	v_mul_f32_e32 v89, 0xbfb8aa3b, v79
	v_mul_f32_e32 v90, 0xbfb8aa3b, v65
	v_mul_f32_e32 v91, 0xbfb8aa3b, v73
	v_exp_f32_e32 v92, v92
	v_exp_f32_e32 v84, v84
	v_exp_f32_e32 v86, v86
	v_exp_f32_e32 v87, v87
	v_exp_f32_e32 v88, v88
	v_exp_f32_e32 v89, v89
	v_exp_f32_e32 v90, v90
	v_exp_f32_e32 v91, v91
	v_add_f32_e32 v92, 1.0, v92
	v_add_f32_e32 v84, 1.0, v84
	v_add_f32_e32 v86, 1.0, v86
	v_add_f32_e32 v87, 1.0, v87
	v_add_f32_e32 v88, 1.0, v88
	v_add_f32_e32 v89, 1.0, v89
	v_add_f32_e32 v90, 1.0, v90
	v_add_f32_e32 v91, 1.0, v91
	v_rcp_f32_e32 v92, v92
	v_rcp_f32_e32 v84, v84
	v_rcp_f32_e32 v86, v86
	v_rcp_f32_e32 v87, v87
	v_rcp_f32_e32 v88, v88
	v_rcp_f32_e32 v89, v89
	v_rcp_f32_e32 v90, v90
	v_rcp_f32_e32 v91, v91
	v_mul_f32_e32 v67, v67, v92
	v_mul_f32_e32 v81, v81, v84
	v_mul_f32_e32 v69, v69, v86
	v_mul_f32_e32 v77, v77, v87
	v_mul_f32_e32 v71, v71, v88
	v_mul_f32_e32 v79, v79, v89
	v_mul_f32_e32 v65, v65, v90
	v_mul_f32_e32 v73, v73, v91
	v_mul_f32_e32 v67, v66, v67
	v_mul_f32_e32 v80, v80, v81
	v_mul_f32_e32 v68, v68, v69
	v_mul_f32_e32 v69, v76, v77
	v_mul_f32_e32 v70, v70, v71
	v_mul_f32_e32 v71, v78, v79
	v_mul_f32_e32 v76, v64, v65
	v_mul_f32_e32 v72, v72, v73
	v_cvt_pk_bf16_f32 v64, v80, v68
	v_cvt_pk_bf16_f32 v65, v69, v70
	v_cvt_pk_bf16_f32 v66, v71, v76
	v_cvt_pk_bf16_f32 v67, v72, v67
	global_store_dwordx4 v[82:83], v[64:67], off
	s_nop 1
	v_mov_b32_e32 v66, v243
	v_add_u32_e32 v69, 0x90, v151
	v_mov_b32_e32 v65, v52
	v_mov_b32_e32 v52, v61
	v_mov_b32_e32 v61, v54
	v_mov_b32_e32 v54, v63
	v_mov_b32_e32 v63, v48
	v_mov_b32_e32 v48, v57
	v_mov_b32_e32 v57, v50
	v_mov_b32_e32 v50, v59
	v_mov_b32_e32 v64, v60
	v_mov_b32_e32 v60, v62
	v_mov_b32_e32 v62, v56
	v_mov_b32_e32 v56, v58
	v_add_u32_e32 v58, s4, v69
	v_ashrrev_i32_e32 v59, 31, v58
	v_lshl_add_u64 v[58:59], v[58:59], 2, s[14:15]
	v_fmamk_f32 v66, v66, 0x3a800000, v150
	v_mul_f32_e32 v67, 0x4b800000, v66
	v_cmp_gt_f32_e32 vcc, s58, v66
	s_nop 1
	v_cndmask_b32_e32 v66, v66, v67, vcc
	v_rsq_f32_e32 v68, v66
	v_mad_i64_i32 v[66:67], s[30:31], v85, s59, v[120:121]
	v_mul_f32_e32 v70, 0x45800000, v68
	v_cndmask_b32_e32 v68, v68, v70, vcc
	v_pk_mul_f32 v[50:51], v[50:51], v[68:69] op_sel_hi:[1,0]
	v_pk_mul_f32 v[64:65], v[64:65], v[68:69] op_sel_hi:[1,0]
	v_pk_mul_f32 v[52:53], v[52:53], v[68:69] op_sel_hi:[1,0]
	v_pk_mul_f32 v[60:61], v[60:61], v[68:69] op_sel_hi:[1,0]
	v_pk_mul_f32 v[54:55], v[54:55], v[68:69] op_sel_hi:[1,0]
	v_pk_mul_f32 v[62:63], v[62:63], v[68:69] op_sel_hi:[1,0]
	v_pk_mul_f32 v[48:49], v[48:49], v[68:69] op_sel_hi:[1,0]
	v_pk_mul_f32 v[56:57], v[56:57], v[68:69] op_sel_hi:[1,0]
	v_mul_f32_e32 v76, 0xbfb8aa3b, v51
	v_mul_f32_e32 v68, 0xbfb8aa3b, v65
	v_mul_f32_e32 v70, 0xbfb8aa3b, v53
	v_mul_f32_e32 v71, 0xbfb8aa3b, v61
	v_mul_f32_e32 v72, 0xbfb8aa3b, v55
	v_mul_f32_e32 v73, 0xbfb8aa3b, v63
	v_mul_f32_e32 v74, 0xbfb8aa3b, v49
	v_mul_f32_e32 v75, 0xbfb8aa3b, v57
	v_exp_f32_e32 v76, v76
	v_exp_f32_e32 v68, v68
	v_exp_f32_e32 v70, v70
	v_exp_f32_e32 v71, v71
	v_exp_f32_e32 v72, v72
	v_exp_f32_e32 v73, v73
	v_exp_f32_e32 v74, v74
	v_exp_f32_e32 v75, v75
	v_add_f32_e32 v76, 1.0, v76
	v_add_f32_e32 v68, 1.0, v68
	v_add_f32_e32 v70, 1.0, v70
	v_add_f32_e32 v71, 1.0, v71
	v_add_f32_e32 v72, 1.0, v72
	v_add_f32_e32 v73, 1.0, v73
	v_add_f32_e32 v74, 1.0, v74
	v_add_f32_e32 v75, 1.0, v75
	v_rcp_f32_e32 v76, v76
	v_rcp_f32_e32 v68, v68
	v_rcp_f32_e32 v70, v70
	v_rcp_f32_e32 v71, v71
	v_rcp_f32_e32 v72, v72
	v_rcp_f32_e32 v73, v73
	v_rcp_f32_e32 v74, v74
	v_rcp_f32_e32 v75, v75
	v_mul_f32_e32 v51, v51, v76
	v_mul_f32_e32 v65, v65, v68
	v_mul_f32_e32 v53, v53, v70
	v_mul_f32_e32 v61, v61, v71
	v_mul_f32_e32 v55, v55, v72
	v_mul_f32_e32 v63, v63, v73
	v_mul_f32_e32 v49, v49, v74
	v_mul_f32_e32 v57, v57, v75
	v_mul_f32_e32 v51, v50, v51
	v_mul_f32_e32 v64, v64, v65
	v_mul_f32_e32 v52, v52, v53
	v_mul_f32_e32 v53, v60, v61
	v_mul_f32_e32 v54, v54, v55
	v_mul_f32_e32 v55, v62, v63
	v_mul_f32_e32 v60, v48, v49
	v_mul_f32_e32 v56, v56, v57
	v_cvt_pk_bf16_f32 v48, v64, v52
	v_cvt_pk_bf16_f32 v49, v53, v54
	v_cvt_pk_bf16_f32 v50, v55, v60
	v_cvt_pk_bf16_f32 v51, v56, v51
	global_store_dwordx4 v[66:67], v[48:51], off
	s_nop 1
	v_mov_b32_e32 v50, v244
	v_add_u32_e32 v53, 0xa0, v151
	v_mov_b32_e32 v49, v36
	v_mov_b32_e32 v36, v45
	v_mov_b32_e32 v45, v38
	v_mov_b32_e32 v38, v47
	v_mov_b32_e32 v47, v32
	v_mov_b32_e32 v32, v41
	v_mov_b32_e32 v41, v34
	v_mov_b32_e32 v34, v43
	v_mov_b32_e32 v48, v44
	v_mov_b32_e32 v44, v46
	v_mov_b32_e32 v46, v40
	v_mov_b32_e32 v40, v42
	v_add_u32_e32 v42, s4, v53
	v_ashrrev_i32_e32 v43, 31, v42
	v_lshl_add_u64 v[42:43], v[42:43], 2, s[14:15]
	v_fmamk_f32 v50, v50, 0x3a800000, v150
	v_mul_f32_e32 v51, 0x4b800000, v50
	v_cmp_gt_f32_e32 vcc, s58, v50
	s_nop 1
	v_cndmask_b32_e32 v50, v50, v51, vcc
	v_rsq_f32_e32 v52, v50
	v_mad_i64_i32 v[50:51], s[30:31], v69, s59, v[120:121]
	v_mul_f32_e32 v54, 0x45800000, v52
	v_cndmask_b32_e32 v52, v52, v54, vcc
	v_pk_mul_f32 v[34:35], v[34:35], v[52:53] op_sel_hi:[1,0]
	v_pk_mul_f32 v[48:49], v[48:49], v[52:53] op_sel_hi:[1,0]
	v_pk_mul_f32 v[36:37], v[36:37], v[52:53] op_sel_hi:[1,0]
	v_pk_mul_f32 v[44:45], v[44:45], v[52:53] op_sel_hi:[1,0]
	v_pk_mul_f32 v[38:39], v[38:39], v[52:53] op_sel_hi:[1,0]
	v_pk_mul_f32 v[46:47], v[46:47], v[52:53] op_sel_hi:[1,0]
	v_pk_mul_f32 v[32:33], v[32:33], v[52:53] op_sel_hi:[1,0]
; __device__ __forceinline__ void st8(bf16_t* p, f32x4 a, f32x4 b) { u32x4 w; w.x = cvt_pk_bf16(a[0], a[1]); w.y = cvt_pk_bf16(a[2], a[3]); w.z = cvt_pk_bf16(b[0], b[1]); w.w = cvt_pk_bf16(b[2], b[3]); *(u32x4*)p = w; }
;     __device__ __forceinline__ void operator()(const f32x4 (&acc)[2][2][4][2], const Unit& u, int wr, int wc, int fr, int fq) const {
;     ...
;                 const int rl = rl0 + ai * HALF + m * 16;
;                 const float s = rsqrtf(ssqX[u.pm * BM + rl] * (1.0f / 1024.0f) + EPS);
;                 f32x4 o[2];
; #pragma unroll
;                 for (int n = 0; n < 2; ++n) {
;                     const f32x4 g = acc[ai][0][m][n] * s, up = acc[ai][1][m][n] * s;
; #pragma unroll
;                     for (int j = 0; j < 4; ++j) { const float e = __builtin_amdgcn_exp2f(g[j] * -1.4426950408889634f); o[n][j] = g[j] * __builtin_amdgcn_rcpf(1.0f + e) * up[j]; }
;                 }
;                 st8(base + (size_t)rl * 2816 + pn * 128 + cw, o[0], o[1]);
;                 asm volatile("" ::: "memory");
	v_pk_mul_f32 v[40:41], v[40:41], v[52:53] op_sel_hi:[1,0]
	v_mul_f32_e32 v60, 0xbfb8aa3b, v35
	v_mul_f32_e32 v52, 0xbfb8aa3b, v49
	v_mul_f32_e32 v54, 0xbfb8aa3b, v37
	v_mul_f32_e32 v55, 0xbfb8aa3b, v45
	v_mul_f32_e32 v56, 0xbfb8aa3b, v39
	v_mul_f32_e32 v57, 0xbfb8aa3b, v47
	v_mul_f32_e32 v58, 0xbfb8aa3b, v33
	v_mul_f32_e32 v59, 0xbfb8aa3b, v41
	v_exp_f32_e32 v60, v60
	v_exp_f32_e32 v52, v52
	v_exp_f32_e32 v54, v54
	v_exp_f32_e32 v55, v55
	v_exp_f32_e32 v56, v56
	v_exp_f32_e32 v57, v57
	v_exp_f32_e32 v58, v58
	v_exp_f32_e32 v59, v59
	v_add_f32_e32 v60, 1.0, v60
	v_add_f32_e32 v52, 1.0, v52
	v_add_f32_e32 v54, 1.0, v54
	v_add_f32_e32 v55, 1.0, v55
	v_add_f32_e32 v56, 1.0, v56
	v_add_f32_e32 v57, 1.0, v57
	v_add_f32_e32 v58, 1.0, v58
	v_add_f32_e32 v59, 1.0, v59
	v_rcp_f32_e32 v60, v60
	v_rcp_f32_e32 v52, v52
	v_rcp_f32_e32 v54, v54
	v_rcp_f32_e32 v55, v55
	v_rcp_f32_e32 v56, v56
	v_rcp_f32_e32 v57, v57
	v_rcp_f32_e32 v58, v58
	v_rcp_f32_e32 v59, v59
	v_mul_f32_e32 v35, v35, v60
	v_mul_f32_e32 v49, v49, v52
	v_mul_f32_e32 v37, v37, v54
	v_mul_f32_e32 v45, v45, v55
	v_mul_f32_e32 v39, v39, v56
	v_mul_f32_e32 v47, v47, v57
	v_mul_f32_e32 v33, v33, v58
	v_mul_f32_e32 v41, v41, v59
	v_mul_f32_e32 v35, v34, v35
	v_mul_f32_e32 v48, v48, v49
	v_mul_f32_e32 v36, v36, v37
	v_mul_f32_e32 v37, v44, v45
	v_mul_f32_e32 v38, v38, v39
	v_mul_f32_e32 v39, v46, v47
	v_mul_f32_e32 v44, v32, v33
	v_mul_f32_e32 v40, v40, v41
	v_cvt_pk_bf16_f32 v32, v48, v36
	v_cvt_pk_bf16_f32 v33, v37, v38
	v_cvt_pk_bf16_f32 v34, v39, v44
	v_cvt_pk_bf16_f32 v35, v40, v35
	global_store_dwordx4 v[50:51], v[32:35], off
	s_nop 1
	v_mov_b32_e32 v34, v245
	v_add_u32_e32 v37, 0xb0, v151
	v_mov_b32_e32 v33, v20
	v_mov_b32_e32 v20, v29
	v_mov_b32_e32 v29, v22
	v_mov_b32_e32 v22, v31
	v_mov_b32_e32 v31, v16
	v_mov_b32_e32 v16, v25
	v_mov_b32_e32 v25, v18
	v_mov_b32_e32 v18, v27
	v_mov_b32_e32 v32, v28
	v_mov_b32_e32 v28, v30
	v_mov_b32_e32 v30, v24
	v_mov_b32_e32 v24, v26
	v_add_u32_e32 v26, s4, v37
	v_ashrrev_i32_e32 v27, 31, v26
	v_lshl_add_u64 v[26:27], v[26:27], 2, s[14:15]
	v_fmamk_f32 v34, v34, 0x3a800000, v150
	v_mul_f32_e32 v35, 0x4b800000, v34
	v_cmp_gt_f32_e32 vcc, s58, v34
	s_nop 1
	v_cndmask_b32_e32 v34, v34, v35, vcc
	v_rsq_f32_e32 v36, v34
	v_mad_i64_i32 v[34:35], s[4:5], v53, s59, v[120:121]
	v_mul_f32_e32 v38, 0x45800000, v36
	v_cndmask_b32_e32 v36, v36, v38, vcc
	v_pk_mul_f32 v[18:19], v[18:19], v[36:37] op_sel_hi:[1,0]
	v_pk_mul_f32 v[32:33], v[32:33], v[36:37] op_sel_hi:[1,0]
	v_pk_mul_f32 v[20:21], v[20:21], v[36:37] op_sel_hi:[1,0]
	v_pk_mul_f32 v[28:29], v[28:29], v[36:37] op_sel_hi:[1,0]
	v_pk_mul_f32 v[22:23], v[22:23], v[36:37] op_sel_hi:[1,0]
	v_pk_mul_f32 v[30:31], v[30:31], v[36:37] op_sel_hi:[1,0]
	v_pk_mul_f32 v[16:17], v[16:17], v[36:37] op_sel_hi:[1,0]
	v_pk_mul_f32 v[24:25], v[24:25], v[36:37] op_sel_hi:[1,0]
	v_mul_f32_e32 v44, 0xbfb8aa3b, v19
	v_mul_f32_e32 v36, 0xbfb8aa3b, v33
	v_mul_f32_e32 v38, 0xbfb8aa3b, v21
	v_mul_f32_e32 v39, 0xbfb8aa3b, v29
	v_mul_f32_e32 v40, 0xbfb8aa3b, v23
	v_mul_f32_e32 v41, 0xbfb8aa3b, v31
	v_mul_f32_e32 v42, 0xbfb8aa3b, v17
	v_mul_f32_e32 v43, 0xbfb8aa3b, v25
	v_exp_f32_e32 v44, v44
	v_exp_f32_e32 v36, v36
	v_exp_f32_e32 v38, v38
	v_exp_f32_e32 v39, v39
	v_exp_f32_e32 v40, v40
	v_exp_f32_e32 v41, v41
	v_exp_f32_e32 v42, v42
	v_exp_f32_e32 v43, v43
	v_add_f32_e32 v44, 1.0, v44
	v_add_f32_e32 v36, 1.0, v36
	v_add_f32_e32 v38, 1.0, v38
	v_add_f32_e32 v39, 1.0, v39
	v_add_f32_e32 v40, 1.0, v40
	v_add_f32_e32 v41, 1.0, v41
	v_add_f32_e32 v42, 1.0, v42
	v_add_f32_e32 v43, 1.0, v43
	v_rcp_f32_e32 v44, v44
	v_rcp_f32_e32 v36, v36
	v_rcp_f32_e32 v38, v38
	v_rcp_f32_e32 v39, v39
	v_rcp_f32_e32 v40, v40
	v_rcp_f32_e32 v41, v41
	v_rcp_f32_e32 v42, v42
	v_rcp_f32_e32 v43, v43
	v_mul_f32_e32 v19, v19, v44
	v_mul_f32_e32 v33, v33, v36
	v_mul_f32_e32 v21, v21, v38
	v_mul_f32_e32 v29, v29, v39
	v_mul_f32_e32 v23, v23, v40
	v_mul_f32_e32 v31, v31, v41
	v_mul_f32_e32 v17, v17, v42
	v_mul_f32_e32 v25, v25, v43
	v_mul_f32_e32 v19, v18, v19
	v_mul_f32_e32 v32, v32, v33
	v_mul_f32_e32 v20, v20, v21
	v_mul_f32_e32 v21, v28, v29
	v_mul_f32_e32 v22, v22, v23
	v_mul_f32_e32 v23, v30, v31
	v_mul_f32_e32 v28, v16, v17
	v_mul_f32_e32 v24, v24, v25
	v_cvt_pk_bf16_f32 v16, v32, v20
	v_cvt_pk_bf16_f32 v17, v21, v22
	v_cvt_pk_bf16_f32 v18, v23, v28
	v_cvt_pk_bf16_f32 v19, v24, v19
	global_store_dwordx4 v[34:35], v[16:19], off
	s_nop 1
	v_mov_b32_e32 v18, v246
	s_nop 0
	v_mov_b32_e32 v17, v4
	v_mov_b32_e32 v4, v13
	v_mov_b32_e32 v13, v6
	v_mov_b32_e32 v6, v15
	v_mov_b32_e32 v15, v0
	v_mov_b32_e32 v0, v9
	v_mov_b32_e32 v9, v2
	v_mov_b32_e32 v16, v12
	v_mov_b32_e32 v12, v14
	v_mov_b32_e32 v14, v8
	v_mov_b32_e32 v8, v10
	v_fmamk_f32 v2, v18, 0x3a800000, v150
	v_mul_f32_e32 v10, 0x4b800000, v2
	v_cmp_gt_f32_e32 vcc, s58, v2
	s_nop 1
	v_cndmask_b32_e32 v2, v2, v10, vcc
	v_rsq_f32_e32 v18, v2
	v_mov_b32_e32 v2, v11
	v_mad_i64_i32 v[10:11], s[4:5], v37, s59, v[120:121]
	v_mul_f32_e32 v19, 0x45800000, v18
	v_cndmask_b32_e32 v18, v18, v19, vcc
	v_pk_mul_f32 v[2:3], v[2:3], v[18:19] op_sel_hi:[1,0]
	v_pk_mul_f32 v[16:17], v[16:17], v[18:19] op_sel_hi:[1,0]
	v_pk_mul_f32 v[4:5], v[4:5], v[18:19] op_sel_hi:[1,0]
	v_pk_mul_f32 v[12:13], v[12:13], v[18:19] op_sel_hi:[1,0]
	v_pk_mul_f32 v[6:7], v[6:7], v[18:19] op_sel_hi:[1,0]
	v_pk_mul_f32 v[14:15], v[14:15], v[18:19] op_sel_hi:[1,0]
	v_pk_mul_f32 v[0:1], v[0:1], v[18:19] op_sel_hi:[1,0]
	v_pk_mul_f32 v[8:9], v[8:9], v[18:19] op_sel_hi:[1,0]
	v_mul_f32_e32 v25, 0xbfb8aa3b, v3
	v_mul_f32_e32 v18, 0xbfb8aa3b, v17
	v_mul_f32_e32 v19, 0xbfb8aa3b, v5
	v_mul_f32_e32 v20, 0xbfb8aa3b, v13
	v_mul_f32_e32 v21, 0xbfb8aa3b, v7
	v_mul_f32_e32 v22, 0xbfb8aa3b, v15
	v_mul_f32_e32 v23, 0xbfb8aa3b, v1
	v_mul_f32_e32 v24, 0xbfb8aa3b, v9
	v_exp_f32_e32 v25, v25
	v_exp_f32_e32 v18, v18
	v_exp_f32_e32 v19, v19
	v_exp_f32_e32 v20, v20
	v_exp_f32_e32 v21, v21
	v_exp_f32_e32 v22, v22
	v_exp_f32_e32 v23, v23
	v_exp_f32_e32 v24, v24
	v_add_f32_e32 v25, 1.0, v25
	v_add_f32_e32 v18, 1.0, v18
	v_add_f32_e32 v19, 1.0, v19
	v_add_f32_e32 v20, 1.0, v20
	v_add_f32_e32 v21, 1.0, v21
	v_add_f32_e32 v22, 1.0, v22
	v_add_f32_e32 v23, 1.0, v23
	v_add_f32_e32 v24, 1.0, v24
	v_rcp_f32_e32 v25, v25
	v_rcp_f32_e32 v18, v18
	v_rcp_f32_e32 v19, v19
	v_rcp_f32_e32 v20, v20
	v_rcp_f32_e32 v21, v21
	v_rcp_f32_e32 v22, v22
	v_rcp_f32_e32 v23, v23
	v_rcp_f32_e32 v24, v24
	v_mul_f32_e32 v3, v3, v25
	v_mul_f32_e32 v17, v17, v18
	v_mul_f32_e32 v5, v5, v19
	v_mul_f32_e32 v13, v13, v20
	v_mul_f32_e32 v7, v7, v21
	v_mul_f32_e32 v15, v15, v22
	v_mul_f32_e32 v1, v1, v23
	v_mul_f32_e32 v9, v9, v24
	v_mul_f32_e32 v3, v2, v3
	v_mul_f32_e32 v16, v16, v17
	v_mul_f32_e32 v4, v4, v5
	v_mul_f32_e32 v5, v12, v13
	v_mul_f32_e32 v6, v6, v7
	v_mul_f32_e32 v7, v14, v15
	v_mul_f32_e32 v12, v0, v1
	v_mul_f32_e32 v8, v8, v9
	v_cvt_pk_bf16_f32 v0, v16, v4
	v_cvt_pk_bf16_f32 v1, v5, v6
	v_cvt_pk_bf16_f32 v2, v7, v12
	v_cvt_pk_bf16_f32 v3, v8, v3
	global_store_dwordx4 v[10:11], v[0:3], off
	s_and_b64 vcc, exec, s[2:3]
	s_mov_b64 s[2:3], -1
	s_cbranch_vccnz .LBB0_801
; #define PG8_BAR __builtin_amdgcn_s_barrier()
; template <class Epi, class Sched, bool ALIGN_EPI = false, bool SP2 = false>
; __device__ __forceinline__ void gemm_phase(PG8_LAS unsigned char* lds, const Gemm g, const Sched& S, const Epi& E) {
;     ...
;         if constexpr (!Epi::AFTER_DRAIN) { E(acc, cur, wr, wc, fr, fq); S.done(cur); }
;         if (!has_next) break;
; #pragma unroll
;         for (int a = 0; a < 2; ++a)
; #pragma unroll
;             for (int b = 0; b < 2; ++b)
; #pragma unroll
;                 for (int m = 0; m < 4; ++m)
; #pragma unroll
;                     for (int n = 0; n < 2; ++n) acc[a][b][m][n] = (f32x4){0.f, 0.f, 0.f, 0.f};
;         cur = nxt; cA = nA; cB = nB; ++ui;
;         if constexpr (ALIGN_EPI) { if (wr == 1) PG8_BAR; }
;     }
	s_andn2_b64 vcc, exec, s[12:13]
	s_cbranch_vccnz .LBB0_800
	s_barrier
	s_branch .LBB0_800

; __device__ __forceinline__ void st8(bf16_t* p, f32x4 a, f32x4 b) { u32x4 w; w.x = cvt_pk_bf16(a[0], a[1]); w.y = cvt_pk_bf16(a[2], a[3]); w.z = cvt_pk_bf16(b[0], b[1]); w.w = cvt_pk_bf16(b[2], b[3]); *(u32x4*)p = w; }
;     __device__ __forceinline__ void operator()(const f32x4 (&acc)[2][2][4][2], const Unit& u, int wr, int wc, int fr, int fq) const {
;         asm volatile("" : "+v"(fr), "+v"(fq)); asm volatile("" : "+s"(wr), "+s"(wc));
;         const int rl0 = wr * 64 + fr, pn = u.pn, cw = wc * 32 + fq * 8;
;         bf16_t* base = (u.pm < pm_split) ? ACT1 + (size_t)u.pm * BM * 2816 : ACT2 + (size_t)(u.pm - pm_split) * BM * 2816;
; #pragma unroll
;         for (int ai = 0; ai < 2; ++ai)
; #pragma unroll
;             for (int m = 0; m < 4; ++m) {
;                 const int rl = rl0 + ai * HALF + m * 16;
;                 const float s = rsqrtf(ssqX[u.pm * BM + rl] * (1.0f / 1024.0f) + EPS);
;                 f32x4 o[2];
; #pragma unroll
;                 for (int n = 0; n < 2; ++n) {
;                     const f32x4 g = acc[ai][0][m][n] * s, up = acc[ai][1][m][n] * s;
; #pragma unroll
;                     for (int j = 0; j < 4; ++j) { const float e = __builtin_amdgcn_exp2f(g[j] * -1.4426950408889634f); o[n][j] = g[j] * __builtin_amdgcn_rcpf(1.0f + e) * up[j]; }
;                 }
;                 st8(base + (size_t)rl * 2816 + pn * 128 + cw, o[0], o[1]);
;                 asm volatile("" ::: "memory");
.LBB0_1615:
	s_add_i32 s23, s28, 0xffffff76
	s_ashr_i32 s30, s28, 31
	s_cmpk_lt_i32 s28, 0x8a
	s_cselect_b32 s23, s28, s23
	s_cselect_b32 s30, s30, 0
	s_mul_i32 s30, s30, 0x160000
	s_mul_hi_u32 s35, s23, 0x160000
	v_mov_b32_e32 v151, v144
	v_mov_b32_e32 v156, v145
	s_mov_b32 s5, s52
	s_mov_b32 s4, s42
	s_cselect_b32 s31, s49, s7
	s_cselect_b32 s34, s48, s6
	s_sub_u32 s84, s92, 0xa140000
	s_subb_u32 s85, s93, 0
	s_cmpk_gt_i32 s28, 0xff
	s_cselect_b32 s34, s84, s34
	s_cselect_b32 s31, s85, s31
	s_add_i32 s35, s35, s30
	s_mul_i32 s23, s23, 0x160000
	s_add_u32 s23, s34, s23
	s_addc_u32 s34, s31, s35
	v_lshl_add_u32 v151, s4, 6, v151
	s_lshl_b32 s4, s28, 8
	v_add_u32_e32 v152, s4, v151
	v_ashrrev_i32_e32 v153, 31, v152
	v_lshl_add_u64 v[152:153], v[152:153], 2, s[14:15]
	global_load_dword v157, v[152:153], off
	global_load_dword v240, v[152:153], off offset:64
	global_load_dword v241, v[152:153], off offset:128
	global_load_dword v242, v[152:153], off offset:192
	global_load_dword v243, v[152:153], off offset:512
	global_load_dword v244, v[152:153], off offset:576
	global_load_dword v245, v[152:153], off offset:640
	global_load_dword v246, v[152:153], off offset:704
	v_mov_b32_e32 v154, v122
	v_mov_b32_e32 v155, v114
	v_mov_b32_e32 v114, v123
	v_mov_b32_e32 v152, v124
	v_mov_b32_e32 v124, v126
	v_mov_b32_e32 v126, v120
	v_lshlrev_b32_e32 v120, 3, v156
	v_mov_b32_e32 v153, v116
	v_mov_b32_e32 v116, v125
	v_mov_b32_e32 v125, v118
	v_mov_b32_e32 v118, v127
	v_mov_b32_e32 v127, v112
	v_mov_b32_e32 v112, v121
	s_lshl_b32 s30, s61, 7
	s_ashr_i32 s31, s30, 31
	s_lshl_b64 s[30:31], s[30:31], 1
	v_lshl_add_u32 v120, s5, 5, v120
	s_add_u32 s30, s23, s30
	v_ashrrev_i32_e32 v121, 31, v120
	s_addc_u32 s31, s34, s31
	v_lshl_add_u64 v[120:121], v[120:121], 1, s[30:31]
	s_waitcnt vmcnt(0)
	v_fmamk_f32 v122, v157, 0x3a800000, v150
	v_mul_f32_e32 v123, 0x4b800000, v122
	v_cmp_gt_f32_e32 vcc, s58, v122
	s_nop 1
	v_cndmask_b32_e32 v122, v122, v123, vcc
	v_rsq_f32_e32 v156, v122
	v_mad_i64_i32 v[122:123], s[30:31], v151, s59, v[120:121]
	v_mul_f32_e32 v157, 0x45800000, v156
	v_cndmask_b32_e32 v156, v156, v157, vcc
	v_pk_mul_f32 v[152:153], v[152:153], v[156:157] op_sel_hi:[1,0]
	v_pk_mul_f32 v[116:117], v[116:117], v[156:157] op_sel_hi:[1,0]
	v_pk_mul_f32 v[124:125], v[124:125], v[156:157] op_sel_hi:[1,0]
	v_pk_mul_f32 v[118:119], v[118:119], v[156:157] op_sel_hi:[1,0]
	v_pk_mul_f32 v[126:127], v[126:127], v[156:157] op_sel_hi:[1,0]
	v_pk_mul_f32 v[112:113], v[112:113], v[156:157] op_sel_hi:[1,0]
	v_pk_mul_f32 v[114:115], v[114:115], v[156:157] op_sel_hi:[1,0]
	v_pk_mul_f32 v[154:155], v[154:155], v[156:157] op_sel_hi:[1,0]
	v_mul_f32_e32 v156, 0xbfb8aa3b, v153
	v_mul_f32_e32 v157, 0xbfb8aa3b, v117
	v_mul_f32_e32 v158, 0xbfb8aa3b, v125
	v_mul_f32_e32 v159, 0xbfb8aa3b, v119
	v_mul_f32_e32 v160, 0xbfb8aa3b, v127
	v_mul_f32_e32 v161, 0xbfb8aa3b, v113
	v_mul_f32_e32 v163, 0xbfb8aa3b, v115
	v_mul_f32_e32 v162, 0xbfb8aa3b, v155
	v_exp_f32_e32 v156, v156
	v_exp_f32_e32 v157, v157
	v_exp_f32_e32 v158, v158
	v_exp_f32_e32 v159, v159
	v_exp_f32_e32 v160, v160
	v_exp_f32_e32 v161, v161
	v_exp_f32_e32 v163, v163
	v_exp_f32_e32 v162, v162
	v_add_f32_e32 v156, 1.0, v156
	v_add_f32_e32 v157, 1.0, v157
	v_add_f32_e32 v158, 1.0, v158
	v_add_f32_e32 v159, 1.0, v159
	v_add_f32_e32 v160, 1.0, v160
	v_add_f32_e32 v161, 1.0, v161
	v_add_f32_e32 v163, 1.0, v163
	v_add_f32_e32 v162, 1.0, v162
	v_rcp_f32_e32 v156, v156
	v_rcp_f32_e32 v157, v157
	v_rcp_f32_e32 v158, v158
	v_rcp_f32_e32 v159, v159
	v_rcp_f32_e32 v160, v160
	v_rcp_f32_e32 v161, v161
	v_rcp_f32_e32 v163, v163
	v_rcp_f32_e32 v162, v162
	v_mul_f32_e32 v153, v153, v156
	v_mul_f32_e32 v117, v117, v157
	v_mul_f32_e32 v125, v125, v158
	v_mul_f32_e32 v119, v119, v159
	v_mul_f32_e32 v127, v127, v160
	v_mul_f32_e32 v113, v113, v161
	v_mul_f32_e32 v115, v115, v163
	v_mul_f32_e32 v155, v155, v162
	v_mul_f32_e32 v152, v152, v153
	v_mul_f32_e32 v116, v116, v117
	v_mul_f32_e32 v117, v124, v125
	v_mul_f32_e32 v118, v118, v119
	v_mul_f32_e32 v119, v126, v127
	v_mul_f32_e32 v124, v112, v113
	v_mul_f32_e32 v115, v114, v115
	v_cvt_pk_bf16_f32 v112, v152, v116
	v_cvt_pk_bf16_f32 v113, v117, v118
	v_cvt_pk_bf16_f32 v114, v119, v124
	v_mul_f32_e32 v125, v154, v155
	v_cvt_pk_bf16_f32 v115, v125, v115
	global_store_dwordx4 v[122:123], v[112:115], off
	v_add_u32_e32 v117, 32, v151
	s_nop 0
	v_add_u32_e32 v114, 16, v151
	v_add_u32_e32 v112, s4, v114
	v_ashrrev_i32_e32 v113, 31, v112
	v_lshl_add_u64 v[112:113], v[112:113], 2, s[14:15]
	s_nop 1
	v_mov_b32_e32 v115, v240
	v_mov_b32_e32 v113, v100
	v_mov_b32_e32 v100, v109
	v_mov_b32_e32 v109, v102
	v_mov_b32_e32 v102, v111
	v_mov_b32_e32 v111, v96
	v_mov_b32_e32 v96, v105
	v_mov_b32_e32 v105, v98
	v_mov_b32_e32 v98, v107
	v_mov_b32_e32 v112, v108
	v_mov_b32_e32 v108, v110
	v_mov_b32_e32 v110, v104
	v_mov_b32_e32 v104, v106
	v_add_u32_e32 v106, s4, v117
	v_ashrrev_i32_e32 v107, 31, v106
	v_lshl_add_u64 v[106:107], v[106:107], 2, s[14:15]
	v_fmamk_f32 v115, v115, 0x3a800000, v150
	v_mul_f32_e32 v116, 0x4b800000, v115
	v_cmp_gt_f32_e32 vcc, s58, v115
	s_nop 1
	v_cndmask_b32_e32 v115, v115, v116, vcc
	v_rsq_f32_e32 v116, v115
	v_mad_i64_i32 v[114:115], s[30:31], v114, s59, v[120:121]
	v_mul_f32_e32 v118, 0x45800000, v116
	v_cndmask_b32_e32 v116, v116, v118, vcc
	v_pk_mul_f32 v[98:99], v[98:99], v[116:117] op_sel_hi:[1,0]
	v_pk_mul_f32 v[112:113], v[112:113], v[116:117] op_sel_hi:[1,0]
	v_pk_mul_f32 v[100:101], v[100:101], v[116:117] op_sel_hi:[1,0]
	v_pk_mul_f32 v[108:109], v[108:109], v[116:117] op_sel_hi:[1,0]
	v_pk_mul_f32 v[102:103], v[102:103], v[116:117] op_sel_hi:[1,0]
; __device__ __forceinline__ void st8(bf16_t* p, f32x4 a, f32x4 b) { u32x4 w; w.x = cvt_pk_bf16(a[0], a[1]); w.y = cvt_pk_bf16(a[2], a[3]); w.z = cvt_pk_bf16(b[0], b[1]); w.w = cvt_pk_bf16(b[2], b[3]); *(u32x4*)p = w; }
;     __device__ __forceinline__ void operator()(const f32x4 (&acc)[2][2][4][2], const Unit& u, int wr, int wc, int fr, int fq) const {
;     ...
;                 const int rl = rl0 + ai * HALF + m * 16;
;                 const float s = rsqrtf(ssqX[u.pm * BM + rl] * (1.0f / 1024.0f) + EPS);
;                 f32x4 o[2];
; #pragma unroll
;                 for (int n = 0; n < 2; ++n) {
;                     const f32x4 g = acc[ai][0][m][n] * s, up = acc[ai][1][m][n] * s;
; #pragma unroll
;                     for (int j = 0; j < 4; ++j) { const float e = __builtin_amdgcn_exp2f(g[j] * -1.4426950408889634f); o[n][j] = g[j] * __builtin_amdgcn_rcpf(1.0f + e) * up[j]; }
;                 }
;                 st8(base + (size_t)rl * 2816 + pn * 128 + cw, o[0], o[1]);
;                 asm volatile("" ::: "memory");
	v_pk_mul_f32 v[110:111], v[110:111], v[116:117] op_sel_hi:[1,0]
	v_pk_mul_f32 v[96:97], v[96:97], v[116:117] op_sel_hi:[1,0]
	v_pk_mul_f32 v[104:105], v[104:105], v[116:117] op_sel_hi:[1,0]
	v_mul_f32_e32 v126, 0xbfb8aa3b, v99
	v_mul_f32_e32 v116, 0xbfb8aa3b, v113
	v_mul_f32_e32 v118, 0xbfb8aa3b, v101
	v_mul_f32_e32 v119, 0xbfb8aa3b, v109
	v_mul_f32_e32 v122, 0xbfb8aa3b, v103
	v_mul_f32_e32 v123, 0xbfb8aa3b, v111
	v_mul_f32_e32 v124, 0xbfb8aa3b, v97
	v_mul_f32_e32 v125, 0xbfb8aa3b, v105
	v_exp_f32_e32 v126, v126
	v_exp_f32_e32 v116, v116
	v_exp_f32_e32 v118, v118
	v_exp_f32_e32 v119, v119
	v_exp_f32_e32 v122, v122
	v_exp_f32_e32 v123, v123
	v_exp_f32_e32 v124, v124
	v_exp_f32_e32 v125, v125
	v_add_f32_e32 v126, 1.0, v126
	v_add_f32_e32 v116, 1.0, v116
	v_add_f32_e32 v118, 1.0, v118
	v_add_f32_e32 v119, 1.0, v119
	v_add_f32_e32 v122, 1.0, v122
	v_add_f32_e32 v123, 1.0, v123
	v_add_f32_e32 v124, 1.0, v124
	v_add_f32_e32 v125, 1.0, v125
	v_rcp_f32_e32 v126, v126
	v_rcp_f32_e32 v116, v116
	v_rcp_f32_e32 v118, v118
	v_rcp_f32_e32 v119, v119
	v_rcp_f32_e32 v122, v122
	v_rcp_f32_e32 v123, v123
	v_rcp_f32_e32 v124, v124
	v_rcp_f32_e32 v125, v125
	v_mul_f32_e32 v99, v99, v126
	v_mul_f32_e32 v113, v113, v116
	v_mul_f32_e32 v101, v101, v118
	v_mul_f32_e32 v109, v109, v119
	v_mul_f32_e32 v103, v103, v122
	v_mul_f32_e32 v111, v111, v123
	v_mul_f32_e32 v97, v97, v124
	v_mul_f32_e32 v105, v105, v125
	v_mul_f32_e32 v99, v98, v99
	v_mul_f32_e32 v112, v112, v113
	v_mul_f32_e32 v100, v100, v101
	v_mul_f32_e32 v101, v108, v109
	v_mul_f32_e32 v102, v102, v103
	v_mul_f32_e32 v103, v110, v111
	v_mul_f32_e32 v108, v96, v97
	v_mul_f32_e32 v104, v104, v105
	v_cvt_pk_bf16_f32 v96, v112, v100
	v_cvt_pk_bf16_f32 v97, v101, v102
	v_cvt_pk_bf16_f32 v98, v103, v108
	v_cvt_pk_bf16_f32 v99, v104, v99
	global_store_dwordx4 v[114:115], v[96:99], off
	s_nop 1
	v_mov_b32_e32 v98, v241
	v_add_u32_e32 v101, 48, v151
	v_mov_b32_e32 v97, v84
	v_mov_b32_e32 v84, v93
	v_mov_b32_e32 v93, v86
	v_mov_b32_e32 v86, v95
	v_mov_b32_e32 v95, v80
	v_mov_b32_e32 v80, v89
	v_mov_b32_e32 v89, v82
	v_mov_b32_e32 v82, v91
	v_mov_b32_e32 v96, v92
	v_mov_b32_e32 v92, v94
	v_mov_b32_e32 v94, v88
	v_mov_b32_e32 v88, v90
	v_add_u32_e32 v90, s4, v101
	v_ashrrev_i32_e32 v91, 31, v90
	v_lshl_add_u64 v[90:91], v[90:91], 2, s[14:15]
	v_fmamk_f32 v98, v98, 0x3a800000, v150
	v_mul_f32_e32 v99, 0x4b800000, v98
	v_cmp_gt_f32_e32 vcc, s58, v98
	s_nop 1
	v_cndmask_b32_e32 v98, v98, v99, vcc
	v_rsq_f32_e32 v100, v98
	v_mad_i64_i32 v[98:99], s[30:31], v117, s59, v[120:121]
	v_mul_f32_e32 v102, 0x45800000, v100
	v_cndmask_b32_e32 v100, v100, v102, vcc
	v_pk_mul_f32 v[82:83], v[82:83], v[100:101] op_sel_hi:[1,0]
	v_pk_mul_f32 v[96:97], v[96:97], v[100:101] op_sel_hi:[1,0]
	v_pk_mul_f32 v[84:85], v[84:85], v[100:101] op_sel_hi:[1,0]
	v_pk_mul_f32 v[92:93], v[92:93], v[100:101] op_sel_hi:[1,0]
	v_pk_mul_f32 v[86:87], v[86:87], v[100:101] op_sel_hi:[1,0]
	v_pk_mul_f32 v[94:95], v[94:95], v[100:101] op_sel_hi:[1,0]
	v_pk_mul_f32 v[80:81], v[80:81], v[100:101] op_sel_hi:[1,0]
	v_pk_mul_f32 v[88:89], v[88:89], v[100:101] op_sel_hi:[1,0]
	v_mul_f32_e32 v108, 0xbfb8aa3b, v83
	v_mul_f32_e32 v100, 0xbfb8aa3b, v97
	v_mul_f32_e32 v102, 0xbfb8aa3b, v85
	v_mul_f32_e32 v103, 0xbfb8aa3b, v93
	v_mul_f32_e32 v104, 0xbfb8aa3b, v87
	v_mul_f32_e32 v105, 0xbfb8aa3b, v95
	v_mul_f32_e32 v106, 0xbfb8aa3b, v81
	v_mul_f32_e32 v107, 0xbfb8aa3b, v89
	v_exp_f32_e32 v108, v108
	v_exp_f32_e32 v100, v100
	v_exp_f32_e32 v102, v102
	v_exp_f32_e32 v103, v103
	v_exp_f32_e32 v104, v104
	v_exp_f32_e32 v105, v105
	v_exp_f32_e32 v106, v106
	v_exp_f32_e32 v107, v107
	v_add_f32_e32 v108, 1.0, v108
	v_add_f32_e32 v100, 1.0, v100
	v_add_f32_e32 v102, 1.0, v102
	v_add_f32_e32 v103, 1.0, v103
	v_add_f32_e32 v104, 1.0, v104
	v_add_f32_e32 v105, 1.0, v105
	v_add_f32_e32 v106, 1.0, v106
	v_add_f32_e32 v107, 1.0, v107
	v_rcp_f32_e32 v108, v108
	v_rcp_f32_e32 v100, v100
	v_rcp_f32_e32 v102, v102
	v_rcp_f32_e32 v103, v103
	v_rcp_f32_e32 v104, v104
	v_rcp_f32_e32 v105, v105
	v_rcp_f32_e32 v106, v106
	v_rcp_f32_e32 v107, v107
	v_mul_f32_e32 v83, v83, v108
	v_mul_f32_e32 v97, v97, v100
	v_mul_f32_e32 v85, v85, v102
	v_mul_f32_e32 v93, v93, v103
	v_mul_f32_e32 v87, v87, v104
	v_mul_f32_e32 v95, v95, v105
	v_mul_f32_e32 v81, v81, v106
	v_mul_f32_e32 v89, v89, v107
	v_mul_f32_e32 v83, v82, v83
	v_mul_f32_e32 v96, v96, v97
	v_mul_f32_e32 v84, v84, v85
	v_mul_f32_e32 v85, v92, v93
	v_mul_f32_e32 v86, v86, v87
	v_mul_f32_e32 v87, v94, v95
	v_mul_f32_e32 v92, v80, v81
	v_mul_f32_e32 v88, v88, v89
	v_cvt_pk_bf16_f32 v80, v96, v84
	v_cvt_pk_bf16_f32 v81, v85, v86
	v_cvt_pk_bf16_f32 v82, v87, v92
	v_cvt_pk_bf16_f32 v83, v88, v83
	global_store_dwordx4 v[98:99], v[80:83], off
	s_nop 1
	v_mov_b32_e32 v82, v242
	v_add_u32_e32 v85, 0x80, v151
	v_mov_b32_e32 v81, v68
	v_mov_b32_e32 v68, v77
	v_mov_b32_e32 v77, v70
	v_mov_b32_e32 v70, v79
	v_mov_b32_e32 v79, v64
	v_mov_b32_e32 v64, v73
	v_mov_b32_e32 v73, v66
	v_mov_b32_e32 v66, v75
	v_mov_b32_e32 v80, v76
	v_mov_b32_e32 v76, v78
	v_mov_b32_e32 v78, v72
	v_mov_b32_e32 v72, v74
	v_add_u32_e32 v74, s4, v85
	v_ashrrev_i32_e32 v75, 31, v74
	v_lshl_add_u64 v[74:75], v[74:75], 2, s[14:15]
	v_fmamk_f32 v82, v82, 0x3a800000, v150
	v_mul_f32_e32 v83, 0x4b800000, v82
	v_cmp_gt_f32_e32 vcc, s58, v82
	s_nop 1
	v_cndmask_b32_e32 v82, v82, v83, vcc
	v_rsq_f32_e32 v84, v82
	v_mad_i64_i32 v[82:83], s[30:31], v101, s59, v[120:121]
	v_mul_f32_e32 v86, 0x45800000, v84
	v_cndmask_b32_e32 v84, v84, v86, vcc
	v_pk_mul_f32 v[66:67], v[66:67], v[84:85] op_sel_hi:[1,0]
	v_pk_mul_f32 v[80:81], v[80:81], v[84:85] op_sel_hi:[1,0]
; __device__ __forceinline__ void st8(bf16_t* p, f32x4 a, f32x4 b) { u32x4 w; w.x = cvt_pk_bf16(a[0], a[1]); w.y = cvt_pk_bf16(a[2], a[3]); w.z = cvt_pk_bf16(b[0], b[1]); w.w = cvt_pk_bf16(b[2], b[3]); *(u32x4*)p = w; }
;     __device__ __forceinline__ void operator()(const f32x4 (&acc)[2][2][4][2], const Unit& u, int wr, int wc, int fr, int fq) const {
;     ...
;                 const int rl = rl0 + ai * HALF + m * 16;
;                 const float s = rsqrtf(ssqX[u.pm * BM + rl] * (1.0f / 1024.0f) + EPS);
;                 f32x4 o[2];
; #pragma unroll
;                 for (int n = 0; n < 2; ++n) {
;                     const f32x4 g = acc[ai][0][m][n] * s, up = acc[ai][1][m][n] * s;
; #pragma unroll
;                     for (int j = 0; j < 4; ++j) { const float e = __builtin_amdgcn_exp2f(g[j] * -1.4426950408889634f); o[n][j] = g[j] * __builtin_amdgcn_rcpf(1.0f + e) * up[j]; }
;                 }
;                 st8(base + (size_t)rl * 2816 + pn * 128 + cw, o[0], o[1]);
;                 asm volatile("" ::: "memory");
	v_pk_mul_f32 v[68:69], v[68:69], v[84:85] op_sel_hi:[1,0]
	v_pk_mul_f32 v[76:77], v[76:77], v[84:85] op_sel_hi:[1,0]
	v_pk_mul_f32 v[70:71], v[70:71], v[84:85] op_sel_hi:[1,0]
	v_pk_mul_f32 v[78:79], v[78:79], v[84:85] op_sel_hi:[1,0]
	v_pk_mul_f32 v[64:65], v[64:65], v[84:85] op_sel_hi:[1,0]
	v_pk_mul_f32 v[72:73], v[72:73], v[84:85] op_sel_hi:[1,0]
	v_mul_f32_e32 v92, 0xbfb8aa3b, v67
	v_mul_f32_e32 v84, 0xbfb8aa3b, v81
	v_mul_f32_e32 v86, 0xbfb8aa3b, v69
	v_mul_f32_e32 v87, 0xbfb8aa3b, v77
	v_mul_f32_e32 v88, 0xbfb8aa3b, v71
	v_mul_f32_e32 v89, 0xbfb8aa3b, v79
	v_mul_f32_e32 v90, 0xbfb8aa3b, v65
	v_mul_f32_e32 v91, 0xbfb8aa3b, v73
	v_exp_f32_e32 v92, v92
	v_exp_f32_e32 v84, v84
	v_exp_f32_e32 v86, v86
	v_exp_f32_e32 v87, v87
	v_exp_f32_e32 v88, v88
	v_exp_f32_e32 v89, v89
	v_exp_f32_e32 v90, v90
	v_exp_f32_e32 v91, v91
	v_add_f32_e32 v92, 1.0, v92
	v_add_f32_e32 v84, 1.0, v84
	v_add_f32_e32 v86, 1.0, v86
	v_add_f32_e32 v87, 1.0, v87
	v_add_f32_e32 v88, 1.0, v88
	v_add_f32_e32 v89, 1.0, v89
	v_add_f32_e32 v90, 1.0, v90
	v_add_f32_e32 v91, 1.0, v91
	v_rcp_f32_e32 v92, v92
	v_rcp_f32_e32 v84, v84
	v_rcp_f32_e32 v86, v86
	v_rcp_f32_e32 v87, v87
	v_rcp_f32_e32 v88, v88
	v_rcp_f32_e32 v89, v89
	v_rcp_f32_e32 v90, v90
	v_rcp_f32_e32 v91, v91
	v_mul_f32_e32 v67, v67, v92
	v_mul_f32_e32 v81, v81, v84
	v_mul_f32_e32 v69, v69, v86
	v_mul_f32_e32 v77, v77, v87
	v_mul_f32_e32 v71, v71, v88
	v_mul_f32_e32 v79, v79, v89
	v_mul_f32_e32 v65, v65, v90
	v_mul_f32_e32 v73, v73, v91
	v_mul_f32_e32 v67, v66, v67
	v_mul_f32_e32 v80, v80, v81
	v_mul_f32_e32 v68, v68, v69
	v_mul_f32_e32 v69, v76, v77
	v_mul_f32_e32 v70, v70, v71
	v_mul_f32_e32 v71, v78, v79
	v_mul_f32_e32 v76, v64, v65
	v_mul_f32_e32 v72, v72, v73
	v_cvt_pk_bf16_f32 v64, v80, v68
	v_cvt_pk_bf16_f32 v65, v69, v70
	v_cvt_pk_bf16_f32 v66, v71, v76
	v_cvt_pk_bf16_f32 v67, v72, v67
	global_store_dwordx4 v[82:83], v[64:67], off
	s_nop 1
	v_mov_b32_e32 v66, v243
	v_add_u32_e32 v69, 0x90, v151
	v_mov_b32_e32 v65, v52
	v_mov_b32_e32 v52, v61
	v_mov_b32_e32 v61, v54
	v_mov_b32_e32 v54, v63
	v_mov_b32_e32 v63, v48
	v_mov_b32_e32 v48, v57
	v_mov_b32_e32 v57, v50
	v_mov_b32_e32 v50, v59
	v_mov_b32_e32 v64, v60
	v_mov_b32_e32 v60, v62
	v_mov_b32_e32 v62, v56
	v_mov_b32_e32 v56, v58
	v_add_u32_e32 v58, s4, v69
	v_ashrrev_i32_e32 v59, 31, v58
	v_lshl_add_u64 v[58:59], v[58:59], 2, s[14:15]
	v_fmamk_f32 v66, v66, 0x3a800000, v150
	v_mul_f32_e32 v67, 0x4b800000, v66
	v_cmp_gt_f32_e32 vcc, s58, v66
	s_nop 1
	v_cndmask_b32_e32 v66, v66, v67, vcc
	v_rsq_f32_e32 v68, v66
	v_mad_i64_i32 v[66:67], s[30:31], v85, s59, v[120:121]
	v_mul_f32_e32 v70, 0x45800000, v68
	v_cndmask_b32_e32 v68, v68, v70, vcc
	v_pk_mul_f32 v[50:51], v[50:51], v[68:69] op_sel_hi:[1,0]
	v_pk_mul_f32 v[64:65], v[64:65], v[68:69] op_sel_hi:[1,0]
	v_pk_mul_f32 v[52:53], v[52:53], v[68:69] op_sel_hi:[1,0]
	v_pk_mul_f32 v[60:61], v[60:61], v[68:69] op_sel_hi:[1,0]
	v_pk_mul_f32 v[54:55], v[54:55], v[68:69] op_sel_hi:[1,0]
	v_pk_mul_f32 v[62:63], v[62:63], v[68:69] op_sel_hi:[1,0]
	v_pk_mul_f32 v[48:49], v[48:49], v[68:69] op_sel_hi:[1,0]
	v_pk_mul_f32 v[56:57], v[56:57], v[68:69] op_sel_hi:[1,0]
	v_mul_f32_e32 v76, 0xbfb8aa3b, v51
	v_mul_f32_e32 v68, 0xbfb8aa3b, v65
	v_mul_f32_e32 v70, 0xbfb8aa3b, v53
	v_mul_f32_e32 v71, 0xbfb8aa3b, v61
	v_mul_f32_e32 v72, 0xbfb8aa3b, v55
	v_mul_f32_e32 v73, 0xbfb8aa3b, v63
	v_mul_f32_e32 v74, 0xbfb8aa3b, v49
	v_mul_f32_e32 v75, 0xbfb8aa3b, v57
	v_exp_f32_e32 v76, v76
	v_exp_f32_e32 v68, v68
	v_exp_f32_e32 v70, v70
	v_exp_f32_e32 v71, v71
	v_exp_f32_e32 v72, v72
	v_exp_f32_e32 v73, v73
	v_exp_f32_e32 v74, v74
	v_exp_f32_e32 v75, v75
	v_add_f32_e32 v76, 1.0, v76
	v_add_f32_e32 v68, 1.0, v68
	v_add_f32_e32 v70, 1.0, v70
	v_add_f32_e32 v71, 1.0, v71
	v_add_f32_e32 v72, 1.0, v72
	v_add_f32_e32 v73, 1.0, v73
	v_add_f32_e32 v74, 1.0, v74
	v_add_f32_e32 v75, 1.0, v75
	v_rcp_f32_e32 v76, v76
	v_rcp_f32_e32 v68, v68
	v_rcp_f32_e32 v70, v70
	v_rcp_f32_e32 v71, v71
	v_rcp_f32_e32 v72, v72
	v_rcp_f32_e32 v73, v73
	v_rcp_f32_e32 v74, v74
	v_rcp_f32_e32 v75, v75
	v_mul_f32_e32 v51, v51, v76
	v_mul_f32_e32 v65, v65, v68
	v_mul_f32_e32 v53, v53, v70
	v_mul_f32_e32 v61, v61, v71
	v_mul_f32_e32 v55, v55, v72
	v_mul_f32_e32 v63, v63, v73
	v_mul_f32_e32 v49, v49, v74
	v_mul_f32_e32 v57, v57, v75
	v_mul_f32_e32 v51, v50, v51
	v_mul_f32_e32 v64, v64, v65
	v_mul_f32_e32 v52, v52, v53
	v_mul_f32_e32 v53, v60, v61
	v_mul_f32_e32 v54, v54, v55
	v_mul_f32_e32 v55, v62, v63
	v_mul_f32_e32 v60, v48, v49
	v_mul_f32_e32 v56, v56, v57
	v_cvt_pk_bf16_f32 v48, v64, v52
	v_cvt_pk_bf16_f32 v49, v53, v54
	v_cvt_pk_bf16_f32 v50, v55, v60
	v_cvt_pk_bf16_f32 v51, v56, v51
	global_store_dwordx4 v[66:67], v[48:51], off
	s_nop 1
	v_mov_b32_e32 v50, v244
	v_add_u32_e32 v53, 0xa0, v151
	v_mov_b32_e32 v49, v36
	v_mov_b32_e32 v36, v45
	v_mov_b32_e32 v45, v38
	v_mov_b32_e32 v38, v47
	v_mov_b32_e32 v47, v32
	v_mov_b32_e32 v32, v41
	v_mov_b32_e32 v41, v34
	v_mov_b32_e32 v34, v43
	v_mov_b32_e32 v48, v44
	v_mov_b32_e32 v44, v46
	v_mov_b32_e32 v46, v40
	v_mov_b32_e32 v40, v42
	v_add_u32_e32 v42, s4, v53
	v_ashrrev_i32_e32 v43, 31, v42
	v_lshl_add_u64 v[42:43], v[42:43], 2, s[14:15]
	v_fmamk_f32 v50, v50, 0x3a800000, v150
	v_mul_f32_e32 v51, 0x4b800000, v50
	v_cmp_gt_f32_e32 vcc, s58, v50
	s_nop 1
	v_cndmask_b32_e32 v50, v50, v51, vcc
	v_rsq_f32_e32 v52, v50
	v_mad_i64_i32 v[50:51], s[30:31], v69, s59, v[120:121]
	v_mul_f32_e32 v54, 0x45800000, v52
	v_cndmask_b32_e32 v52, v52, v54, vcc
	v_pk_mul_f32 v[34:35], v[34:35], v[52:53] op_sel_hi:[1,0]
	v_pk_mul_f32 v[48:49], v[48:49], v[52:53] op_sel_hi:[1,0]
	v_pk_mul_f32 v[36:37], v[36:37], v[52:53] op_sel_hi:[1,0]
; __device__ __forceinline__ void st8(bf16_t* p, f32x4 a, f32x4 b) { u32x4 w; w.x = cvt_pk_bf16(a[0], a[1]); w.y = cvt_pk_bf16(a[2], a[3]); w.z = cvt_pk_bf16(b[0], b[1]); w.w = cvt_pk_bf16(b[2], b[3]); *(u32x4*)p = w; }
;     __device__ __forceinline__ void operator()(const f32x4 (&acc)[2][2][4][2], const Unit& u, int wr, int wc, int fr, int fq) const {
;     ...
;                 const int rl = rl0 + ai * HALF + m * 16;
;                 const float s = rsqrtf(ssqX[u.pm * BM + rl] * (1.0f / 1024.0f) + EPS);
;                 f32x4 o[2];
; #pragma unroll
;                 for (int n = 0; n < 2; ++n) {
;                     const f32x4 g = acc[ai][0][m][n] * s, up = acc[ai][1][m][n] * s;
; #pragma unroll
;                     for (int j = 0; j < 4; ++j) { const float e = __builtin_amdgcn_exp2f(g[j] * -1.4426950408889634f); o[n][j] = g[j] * __builtin_amdgcn_rcpf(1.0f + e) * up[j]; }
;                 }
;                 st8(base + (size_t)rl * 2816 + pn * 128 + cw, o[0], o[1]);
;                 asm volatile("" ::: "memory");
	v_pk_mul_f32 v[44:45], v[44:45], v[52:53] op_sel_hi:[1,0]
	v_pk_mul_f32 v[38:39], v[38:39], v[52:53] op_sel_hi:[1,0]
	v_pk_mul_f32 v[46:47], v[46:47], v[52:53] op_sel_hi:[1,0]
	v_pk_mul_f32 v[32:33], v[32:33], v[52:53] op_sel_hi:[1,0]
	v_pk_mul_f32 v[40:41], v[40:41], v[52:53] op_sel_hi:[1,0]
	v_mul_f32_e32 v60, 0xbfb8aa3b, v35
	v_mul_f32_e32 v52, 0xbfb8aa3b, v49
	v_mul_f32_e32 v54, 0xbfb8aa3b, v37
	v_mul_f32_e32 v55, 0xbfb8aa3b, v45
	v_mul_f32_e32 v56, 0xbfb8aa3b, v39
	v_mul_f32_e32 v57, 0xbfb8aa3b, v47
	v_mul_f32_e32 v58, 0xbfb8aa3b, v33
	v_mul_f32_e32 v59, 0xbfb8aa3b, v41
	v_exp_f32_e32 v60, v60
	v_exp_f32_e32 v52, v52
	v_exp_f32_e32 v54, v54
	v_exp_f32_e32 v55, v55
	v_exp_f32_e32 v56, v56
	v_exp_f32_e32 v57, v57
	v_exp_f32_e32 v58, v58
	v_exp_f32_e32 v59, v59
	v_add_f32_e32 v60, 1.0, v60
	v_add_f32_e32 v52, 1.0, v52
	v_add_f32_e32 v54, 1.0, v54
	v_add_f32_e32 v55, 1.0, v55
	v_add_f32_e32 v56, 1.0, v56
	v_add_f32_e32 v57, 1.0, v57
	v_add_f32_e32 v58, 1.0, v58
	v_add_f32_e32 v59, 1.0, v59
	v_rcp_f32_e32 v60, v60
	v_rcp_f32_e32 v52, v52
	v_rcp_f32_e32 v54, v54
	v_rcp_f32_e32 v55, v55
	v_rcp_f32_e32 v56, v56
	v_rcp_f32_e32 v57, v57
	v_rcp_f32_e32 v58, v58
	v_rcp_f32_e32 v59, v59
	v_mul_f32_e32 v35, v35, v60
	v_mul_f32_e32 v49, v49, v52
	v_mul_f32_e32 v37, v37, v54
	v_mul_f32_e32 v45, v45, v55
	v_mul_f32_e32 v39, v39, v56
	v_mul_f32_e32 v47, v47, v57
	v_mul_f32_e32 v33, v33, v58
	v_mul_f32_e32 v41, v41, v59
	v_mul_f32_e32 v35, v34, v35
	v_mul_f32_e32 v48, v48, v49
	v_mul_f32_e32 v36, v36, v37
	v_mul_f32_e32 v37, v44, v45
	v_mul_f32_e32 v38, v38, v39
	v_mul_f32_e32 v39, v46, v47
	v_mul_f32_e32 v44, v32, v33
	v_mul_f32_e32 v40, v40, v41
	v_cvt_pk_bf16_f32 v32, v48, v36
	v_cvt_pk_bf16_f32 v33, v37, v38
	v_cvt_pk_bf16_f32 v34, v39, v44
	v_cvt_pk_bf16_f32 v35, v40, v35
	global_store_dwordx4 v[50:51], v[32:35], off
	s_nop 1
	v_mov_b32_e32 v34, v245
	v_add_u32_e32 v37, 0xb0, v151
	v_mov_b32_e32 v33, v20
	v_mov_b32_e32 v20, v29
	v_mov_b32_e32 v29, v22
	v_mov_b32_e32 v22, v31
	v_mov_b32_e32 v31, v16
	v_mov_b32_e32 v16, v25
	v_mov_b32_e32 v25, v18
	v_mov_b32_e32 v18, v27
	v_mov_b32_e32 v32, v28
	v_mov_b32_e32 v28, v30
	v_mov_b32_e32 v30, v24
	v_mov_b32_e32 v24, v26
	v_add_u32_e32 v26, s4, v37
	v_ashrrev_i32_e32 v27, 31, v26
	v_lshl_add_u64 v[26:27], v[26:27], 2, s[14:15]
	v_fmamk_f32 v34, v34, 0x3a800000, v150
	v_mul_f32_e32 v35, 0x4b800000, v34
	v_cmp_gt_f32_e32 vcc, s58, v34
	s_nop 1
	v_cndmask_b32_e32 v34, v34, v35, vcc
	v_rsq_f32_e32 v36, v34
	v_mad_i64_i32 v[34:35], s[4:5], v53, s59, v[120:121]
	v_mul_f32_e32 v38, 0x45800000, v36
	v_cndmask_b32_e32 v36, v36, v38, vcc
	v_pk_mul_f32 v[18:19], v[18:19], v[36:37] op_sel_hi:[1,0]
	v_pk_mul_f32 v[32:33], v[32:33], v[36:37] op_sel_hi:[1,0]
	v_pk_mul_f32 v[20:21], v[20:21], v[36:37] op_sel_hi:[1,0]
	v_pk_mul_f32 v[28:29], v[28:29], v[36:37] op_sel_hi:[1,0]
	v_pk_mul_f32 v[22:23], v[22:23], v[36:37] op_sel_hi:[1,0]
	v_pk_mul_f32 v[30:31], v[30:31], v[36:37] op_sel_hi:[1,0]
	v_pk_mul_f32 v[16:17], v[16:17], v[36:37] op_sel_hi:[1,0]
	v_pk_mul_f32 v[24:25], v[24:25], v[36:37] op_sel_hi:[1,0]
	v_mul_f32_e32 v44, 0xbfb8aa3b, v19
	v_mul_f32_e32 v36, 0xbfb8aa3b, v33
	v_mul_f32_e32 v38, 0xbfb8aa3b, v21
	v_mul_f32_e32 v39, 0xbfb8aa3b, v29
	v_mul_f32_e32 v40, 0xbfb8aa3b, v23
	v_mul_f32_e32 v41, 0xbfb8aa3b, v31
	v_mul_f32_e32 v42, 0xbfb8aa3b, v17
	v_mul_f32_e32 v43, 0xbfb8aa3b, v25
	v_exp_f32_e32 v44, v44
	v_exp_f32_e32 v36, v36
	v_exp_f32_e32 v38, v38
	v_exp_f32_e32 v39, v39
	v_exp_f32_e32 v40, v40
	v_exp_f32_e32 v41, v41
	v_exp_f32_e32 v42, v42
	v_exp_f32_e32 v43, v43
	v_add_f32_e32 v44, 1.0, v44
	v_add_f32_e32 v36, 1.0, v36
	v_add_f32_e32 v38, 1.0, v38
	v_add_f32_e32 v39, 1.0, v39
; __device__ __forceinline__ void st8(bf16_t* p, f32x4 a, f32x4 b) { u32x4 w; w.x = cvt_pk_bf16(a[0], a[1]); w.y = cvt_pk_bf16(a[2], a[3]); w.z = cvt_pk_bf16(b[0], b[1]); w.w = cvt_pk_bf16(b[2], b[3]); *(u32x4*)p = w; }
; #define PG8_BAR __builtin_amdgcn_s_barrier()
;     __device__ __forceinline__ void operator()(const f32x4 (&acc)[2][2][4][2], const Unit& u, int wr, int wc, int fr, int fq) const {
;     ...
;                 const int rl = rl0 + ai * HALF + m * 16;
;                 const float s = rsqrtf(ssqX[u.pm * BM + rl] * (1.0f / 1024.0f) + EPS);
;                 f32x4 o[2];
; #pragma unroll
;                 for (int n = 0; n < 2; ++n) {
;                     const f32x4 g = acc[ai][0][m][n] * s, up = acc[ai][1][m][n] * s;
; #pragma unroll
;                     for (int j = 0; j < 4; ++j) { const float e = __builtin_amdgcn_exp2f(g[j] * -1.4426950408889634f); o[n][j] = g[j] * __builtin_amdgcn_rcpf(1.0f + e) * up[j]; }
;                 }
;                 st8(base + (size_t)rl * 2816 + pn * 128 + cw, o[0], o[1]);
;                 asm volatile("" ::: "memory");
; template <class Epi, class Sched, bool ALIGN_EPI = false, bool SP2 = false>
; __device__ __forceinline__ void gemm_phase(PG8_LAS unsigned char* lds, const Gemm g, const Sched& S, const Epi& E) {
;     ...
;         if constexpr (!Epi::AFTER_DRAIN) { E(acc, cur, wr, wc, fr, fq); S.done(cur); }
;         if (!has_next) break;
; #pragma unroll
;         for (int a = 0; a < 2; ++a)
; #pragma unroll
;             for (int b = 0; b < 2; ++b)
; #pragma unroll
;                 for (int m = 0; m < 4; ++m)
; #pragma unroll
;                     for (int n = 0; n < 2; ++n) acc[a][b][m][n] = (f32x4){0.f, 0.f, 0.f, 0.f};
;         cur = nxt; cA = nA; cB = nB; ++ui;
;         if constexpr (ALIGN_EPI) { if (wr == 1) PG8_BAR; }
	v_add_f32_e32 v40, 1.0, v40
	v_add_f32_e32 v41, 1.0, v41
	v_add_f32_e32 v42, 1.0, v42
	v_add_f32_e32 v43, 1.0, v43
	v_rcp_f32_e32 v44, v44
	v_rcp_f32_e32 v36, v36
	v_rcp_f32_e32 v38, v38
	v_rcp_f32_e32 v39, v39
	v_rcp_f32_e32 v40, v40
	v_rcp_f32_e32 v41, v41
	v_rcp_f32_e32 v42, v42
	v_rcp_f32_e32 v43, v43
	v_mul_f32_e32 v19, v19, v44
	v_mul_f32_e32 v33, v33, v36
	v_mul_f32_e32 v21, v21, v38
	v_mul_f32_e32 v29, v29, v39
	v_mul_f32_e32 v23, v23, v40
	v_mul_f32_e32 v31, v31, v41
	v_mul_f32_e32 v17, v17, v42
	v_mul_f32_e32 v25, v25, v43
	v_mul_f32_e32 v19, v18, v19
	v_mul_f32_e32 v32, v32, v33
	v_mul_f32_e32 v20, v20, v21
	v_mul_f32_e32 v21, v28, v29
	v_mul_f32_e32 v22, v22, v23
	v_mul_f32_e32 v23, v30, v31
	v_mul_f32_e32 v28, v16, v17
	v_mul_f32_e32 v24, v24, v25
	v_cvt_pk_bf16_f32 v16, v32, v20
	v_cvt_pk_bf16_f32 v17, v21, v22
	v_cvt_pk_bf16_f32 v18, v23, v28
	v_cvt_pk_bf16_f32 v19, v24, v19
	global_store_dwordx4 v[34:35], v[16:19], off
	s_nop 1
	v_mov_b32_e32 v18, v246
	s_nop 0
	v_mov_b32_e32 v17, v4
	v_mov_b32_e32 v4, v13
	v_mov_b32_e32 v13, v6
	v_mov_b32_e32 v6, v15
	v_mov_b32_e32 v15, v0
	v_mov_b32_e32 v0, v9
	v_mov_b32_e32 v9, v2
	v_mov_b32_e32 v16, v12
	v_mov_b32_e32 v12, v14
	v_mov_b32_e32 v14, v8
	v_mov_b32_e32 v8, v10
	v_fmamk_f32 v2, v18, 0x3a800000, v150
	v_mul_f32_e32 v10, 0x4b800000, v2
	v_cmp_gt_f32_e32 vcc, s58, v2
	s_nop 1
	v_cndmask_b32_e32 v2, v2, v10, vcc
	v_rsq_f32_e32 v18, v2
	v_mov_b32_e32 v2, v11
	v_mad_i64_i32 v[10:11], s[4:5], v37, s59, v[120:121]
	v_mul_f32_e32 v19, 0x45800000, v18
	v_cndmask_b32_e32 v18, v18, v19, vcc
	v_pk_mul_f32 v[2:3], v[2:3], v[18:19] op_sel_hi:[1,0]
	v_pk_mul_f32 v[16:17], v[16:17], v[18:19] op_sel_hi:[1,0]
	v_pk_mul_f32 v[4:5], v[4:5], v[18:19] op_sel_hi:[1,0]
	v_pk_mul_f32 v[12:13], v[12:13], v[18:19] op_sel_hi:[1,0]
	v_pk_mul_f32 v[6:7], v[6:7], v[18:19] op_sel_hi:[1,0]
	v_pk_mul_f32 v[14:15], v[14:15], v[18:19] op_sel_hi:[1,0]
	v_pk_mul_f32 v[0:1], v[0:1], v[18:19] op_sel_hi:[1,0]
	v_pk_mul_f32 v[8:9], v[8:9], v[18:19] op_sel_hi:[1,0]
	v_mul_f32_e32 v25, 0xbfb8aa3b, v3
	v_mul_f32_e32 v18, 0xbfb8aa3b, v17
	v_mul_f32_e32 v19, 0xbfb8aa3b, v5
	v_mul_f32_e32 v20, 0xbfb8aa3b, v13
	v_mul_f32_e32 v21, 0xbfb8aa3b, v7
	v_mul_f32_e32 v22, 0xbfb8aa3b, v15
	v_mul_f32_e32 v23, 0xbfb8aa3b, v1
	v_mul_f32_e32 v24, 0xbfb8aa3b, v9
	v_exp_f32_e32 v25, v25
	v_exp_f32_e32 v18, v18
	v_exp_f32_e32 v19, v19
	v_exp_f32_e32 v20, v20
	v_exp_f32_e32 v21, v21
	v_exp_f32_e32 v22, v22
	v_exp_f32_e32 v23, v23
	v_exp_f32_e32 v24, v24
	v_add_f32_e32 v25, 1.0, v25
	v_add_f32_e32 v18, 1.0, v18
	v_add_f32_e32 v19, 1.0, v19
	v_add_f32_e32 v20, 1.0, v20
	v_add_f32_e32 v21, 1.0, v21
	v_add_f32_e32 v22, 1.0, v22
	v_add_f32_e32 v23, 1.0, v23
	v_add_f32_e32 v24, 1.0, v24
	v_rcp_f32_e32 v25, v25
	v_rcp_f32_e32 v18, v18
	v_rcp_f32_e32 v19, v19
	v_rcp_f32_e32 v20, v20
	v_rcp_f32_e32 v21, v21
	v_rcp_f32_e32 v22, v22
	v_rcp_f32_e32 v23, v23
	v_rcp_f32_e32 v24, v24
	v_mul_f32_e32 v3, v3, v25
	v_mul_f32_e32 v17, v17, v18
	v_mul_f32_e32 v5, v5, v19
	v_mul_f32_e32 v13, v13, v20
	v_mul_f32_e32 v7, v7, v21
	v_mul_f32_e32 v15, v15, v22
	v_mul_f32_e32 v1, v1, v23
	v_mul_f32_e32 v9, v9, v24
	v_mul_f32_e32 v3, v2, v3
	v_mul_f32_e32 v16, v16, v17
	v_mul_f32_e32 v4, v4, v5
	v_mul_f32_e32 v5, v12, v13
	v_mul_f32_e32 v6, v6, v7
	v_mul_f32_e32 v7, v14, v15
	v_mul_f32_e32 v12, v0, v1
	v_mul_f32_e32 v8, v8, v9
	v_cvt_pk_bf16_f32 v0, v16, v4
	v_cvt_pk_bf16_f32 v1, v5, v6
	v_cvt_pk_bf16_f32 v2, v7, v12
	v_cvt_pk_bf16_f32 v3, v8, v3
	global_store_dwordx4 v[10:11], v[0:3], off
	s_and_b64 vcc, exec, s[2:3]
	s_mov_b64 s[2:3], -1
	s_cbranch_vccnz .LBB0_1601
	s_andn2_b64 vcc, exec, s[12:13]
	s_cbranch_vccnz .LBB0_1600
	s_barrier
	s_branch .LBB0_1600
